# P2 token-local phase: loop-invariant gain loads hoisted out of the row loop, rotary-table load issued with the row's first loads (one memory round trip per row instead of five)
# speedup vs baseline: 1.0217x; 1.0074x over previous
.LBB0_483:
	s_or_b64 exec, exec, s[0:1]
	v_mov_b32_e32 v70, v0
	s_waitcnt lgkmcnt(0)
	s_barrier
	s_nop 0
	v_readfirstlane_b32 s2, v70
	s_ashr_i32 s0, s2, 6
	s_add_i32 s4, s0, s97
	s_cmp_gt_i32 s4, 0x93ff
	s_cbranch_scc1 .LBB0_502
	v_and_b32_e32 v86, 63, v70
	v_readlane_b32 s44, v253, 60
	v_lshlrev_b32_e32 v88, 4, v86
	v_mov_b32_e32 v89, 0
	v_readlane_b32 s48, v254, 0
	v_readlane_b32 s49, v254, 1
	v_readlane_b32 s50, v254, 2
	v_readlane_b32 s51, v254, 3
	v_lshl_add_u64 v[46:47], s[48:49], 0, v[88:89]
	v_add_co_u32_e32 v26, vcc, 0x1000, v46
	s_nop 0
	global_load_dwordx4 v[2:5], v88, s[48:49] offset:1024
	global_load_dwordx4 v[6:9], v88, s[48:49] offset:2048
	global_load_dwordx4 v[10:13], v88, s[48:49] offset:3072
	v_addc_co_u32_e32 v27, vcc, 0, v47, vcc
	v_add_co_u32_e32 v42, vcc, 0x2000, v46
	global_load_dwordx4 v[14:17], v[26:27], off
	global_load_dwordx4 v[18:21], v[26:27], off offset:1024
	global_load_dwordx4 v[22:25], v[26:27], off offset:2048
	s_nop 0
	global_load_dwordx4 v[26:29], v[26:27], off offset:3072
	v_addc_co_u32_e32 v43, vcc, 0, v47, vcc
	v_add_co_u32_e32 v58, vcc, 0x3000, v46
	global_load_dwordx4 v[30:33], v[42:43], off
	global_load_dwordx4 v[34:37], v[42:43], off offset:1024
	global_load_dwordx4 v[38:41], v[42:43], off offset:2048
	s_nop 0
	global_load_dwordx4 v[42:45], v[42:43], off offset:3072
	v_addc_co_u32_e32 v59, vcc, 0, v47, vcc
	global_load_dwordx4 v[46:49], v[58:59], off
	global_load_dwordx4 v[50:53], v[58:59], off offset:1024
	global_load_dwordx4 v[54:57], v[58:59], off offset:2048
	s_nop 0
	global_load_dwordx4 v[58:61], v[58:59], off offset:3072
	s_nop 0
	global_load_dwordx4 v[62:65], v88, s[48:49]
	global_load_dwordx4 v[66:69], v88, s[50:51]
	v_readlane_b32 s45, v253, 61
	v_readlane_b32 s46, v253, 62
	v_readlane_b32 s47, v253, 63
	v_and_b32_e32 v73, 16, v70
	v_readlane_b32 s16, v254, 12
	v_readlane_b32 s36, v254, 28
	v_lshlrev_b32_e32 v72, 1, v86
	v_cmp_eq_u32_e64 s[8:9], 0, v73
	v_lshlrev_b32_e32 v74, 5, v86
	v_mov_b32_e32 v75, v89
	v_readlane_b32 s17, v254, 13
	v_readlane_b32 s18, v254, 14
	v_readlane_b32 s19, v254, 15
	v_readlane_b32 s20, v254, 16
	v_readlane_b32 s21, v254, 17
	v_readlane_b32 s22, v254, 18
	v_readlane_b32 s23, v254, 19
	v_readlane_b32 s24, v254, 20
	v_readlane_b32 s25, v254, 21
	v_readlane_b32 s26, v254, 22
	v_readlane_b32 s27, v254, 23
	v_readlane_b32 s28, v254, 24
	v_readlane_b32 s29, v254, 25
	v_readlane_b32 s30, v254, 26
	v_readlane_b32 s31, v254, 27
	v_readlane_b32 s37, v254, 29
	v_readlane_b32 s38, v254, 30
	v_readlane_b32 s39, v254, 31
	v_readlane_b32 s40, v254, 32
	v_readlane_b32 s41, v254, 33
	v_readlane_b32 s42, v254, 34
	v_readlane_b32 s43, v254, 35
	v_readlane_b32 s44, v254, 36
	v_readlane_b32 s45, v254, 37
	v_readlane_b32 s46, v254, 38
	v_readlane_b32 s47, v254, 39
	v_readlane_b32 s48, v254, 40
	v_readlane_b32 s49, v254, 41
	v_readlane_b32 s50, v254, 42
	v_readlane_b32 s51, v254, 43
	v_mov_b32_e32 v73, v89
	v_lshl_add_u64 v[92:93], s[22:23], 0, v[74:75]
	v_lshl_add_u64 v[94:95], s[42:43], 0, v[88:89]
	v_lshl_add_u64 v[96:97], s[24:25], 0, v[74:75]
	v_lshl_add_u64 v[98:99], s[44:45], 0, v[88:89]
	v_readlane_b32 s16, v254, 44
	v_lshl_add_u64 v[102:103], s[36:37], 0, v[88:89]
	v_lshl_add_u64 v[104:105], s[38:39], 0, v[88:89]
	v_lshl_add_u64 v[106:107], s[40:41], 0, v[72:73]
	v_readlane_b32 s36, v253, 40
	v_readlane_b32 s17, v254, 45
	v_readlane_b32 s18, v254, 46
	v_readlane_b32 s19, v254, 47
	v_readlane_b32 s20, v254, 48
	v_readlane_b32 s21, v254, 49
	v_readlane_b32 s37, v253, 41
	v_and_b32_e32 v71, 31, v70
	v_readlane_b32 s26, v254, 54
	v_readlane_b32 s27, v254, 55
	v_readlane_b32 s28, v254, 56
	v_readlane_b32 s29, v254, 57
	v_lshlrev_b32_e32 v70, 5, v70
	v_readlane_b32 s38, v253, 42
	v_readlane_b32 s39, v253, 43
	v_readlane_b32 s40, v253, 44
	v_readlane_b32 s41, v253, 45
	v_readlane_b32 s48, v253, 52
	v_readlane_b32 s49, v253, 53
	s_mov_b64 s[16:17], s[36:37]
	v_lshl_add_u64 v[100:101], s[26:27], 0, v[88:89]
	v_and_b32_e32 v88, 0x1e0, v70
	s_mov_b64 s[18:19], s[38:39]
	s_mov_b64 s[28:29], s[48:49]
	v_readlane_b32 s54, v254, 6
	v_readlane_b32 s55, v254, 7
	v_readlane_b32 s56, v254, 8
	v_readlane_b32 s57, v254, 9
	s_bfe_u32 s2, s2, 0x30006
	v_readlane_b32 s24, v254, 52
	v_readlane_b32 s25, v254, 53
	s_mov_b64 s[20:21], s[40:41]
	v_lshl_add_u64 v[108:109], s[28:29], 0, v[88:89]
	v_lshlrev_b32_e32 v88, 2, v71
	s_mov_b32 s18, 0x3d000000
	s_mov_b32 s15, 0
	v_lshlrev_b32_e32 v90, 3, v86
	v_cmp_gt_u32_e64 s[0:1], 48, v86
	v_cmp_gt_u32_e64 s[6:7], 32, v86
	v_and_b32_e32 v87, 30, v72
	s_bitset1_b32 s2, 11
	v_lshl_add_u64 v[110:111], s[54:55], 0, v[74:75]
	v_lshl_add_u64 v[112:113], s[56:57], 0, v[74:75]
	v_lshl_add_u64 v[114:115], s[20:21], 0, v[88:89]
	v_lshl_add_u64 v[116:117], s[24:25], 0, v[74:75]
	v_mov_b32_e32 v118, 0x358637bd
	s_mov_b32 s17, 0x800000
	v_mov_b32_e32 v91, 0xffff
	s_mov_b32 s21, 0xbfb8aa3b
	s_mov_b32 s16, 0xbf317218
	s_mov_b32 s19, 0x3b800000
	v_mov_b32_e32 v119, 0x300
	s_mov_b32 s20, 0x3d800000
	v_readlane_b32 s52, v254, 4
	v_readlane_b32 s53, v254, 5
	v_readlane_b32 s58, v254, 10
	v_readlane_b32 s59, v254, 11
	v_readlane_b32 s22, v254, 50
	v_readlane_b32 s23, v254, 51
	v_readlane_b32 s30, v254, 58
	v_readlane_b32 s31, v254, 59
	v_readlane_b32 s42, v253, 46
	v_readlane_b32 s43, v253, 47
	v_readlane_b32 s44, v253, 48
	v_readlane_b32 s45, v253, 49
	v_readlane_b32 s46, v253, 50
	v_readlane_b32 s47, v253, 51
	v_readlane_b32 s50, v253, 54
	v_readlane_b32 s51, v253, 55
	global_load_dwordx4 v[154:157], v[108:109], off
	global_load_dwordx4 v[158:161], v[108:109], off offset:16
	global_load_dword v152, v[114:115], off
	s_and_saveexec_b64 s[12:13], s[0:1]
	global_load_dwordx4 v[136:139], v[110:111], off
	global_load_dwordx4 v[140:143], v[110:111], off offset:16
	s_and_b64 exec, exec, s[6:7]
	global_load_dwordx4 v[144:147], v[112:113], off
	global_load_dwordx4 v[148:151], v[112:113], off offset:16
	s_mov_b64 exec, s[12:13]
	s_waitcnt vmcnt(0)
	s_branch .LBB0_487

.LBB0_487:
	s_mov_b64 s[10:11], -1
	s_cmp_gt_i32 s4, 0x83ff
	v_mbcnt_hi_u32_b32 v122, -1, v1
	s_cbranch_scc0 .LBB0_489
	s_add_i32 s14, s4, 0xffff7c00
	s_lshl_b64 s[10:11], s[14:15], 12
	v_lshl_add_u64 v[74:75], v[116:117], 0, s[10:11]
	global_load_dwordx4 v[78:81], v[74:75], off offset:16
	global_load_dwordx4 v[82:85], v[74:75], off
	s_waitcnt lgkmcnt(0)
	global_load_dwordx4 v[70:73], v[74:75], off offset:2064
	s_nop 0
	global_load_dwordx4 v[74:77], v[74:75], off offset:2048
	s_lshl_b64 s[10:11], s[14:15], 11
	s_lshl_b64 s[12:13], s[14:15], 10
	s_waitcnt vmcnt(3)
	v_pk_mul_f32 v[124:125], v[78:79], v[78:79]
	s_waitcnt vmcnt(2)
	v_mul_f32_e32 v88, v83, v83
	v_fmac_f32_e32 v88, v82, v82
	v_pk_mul_f32 v[120:121], v[84:85], v[84:85]
	s_nop 0
	v_add_f32_e32 v88, v120, v88
	v_add_f32_e32 v88, v121, v88
	v_add_f32_e32 v88, v124, v88
	v_add_f32_e32 v88, v125, v88
	v_pk_mul_f32 v[120:121], v[80:81], v[80:81]
	s_nop 0
	v_add_f32_e32 v88, v120, v88
	v_add_f32_e32 v88, v121, v88
	v_and_b32_e32 v121, 64, v122
	v_xor_b32_e32 v120, 1, v122
	v_add_u32_e32 v121, 64, v121
	v_cmp_lt_i32_e32 vcc, v120, v121
	s_nop 1
	v_cndmask_b32_e32 v120, v122, v120, vcc
	v_lshlrev_b32_e32 v120, 2, v120
	ds_bpermute_b32 v120, v120, v88
	s_waitcnt lgkmcnt(0)
	v_add_f32_e32 v88, v88, v120
	v_xor_b32_e32 v120, 2, v122
	v_cmp_lt_i32_e32 vcc, v120, v121
	s_nop 1
	v_cndmask_b32_e32 v120, v122, v120, vcc
	v_lshlrev_b32_e32 v120, 2, v120
	ds_bpermute_b32 v120, v120, v88
	s_waitcnt lgkmcnt(0)
	v_add_f32_e32 v88, v88, v120
	v_xor_b32_e32 v120, 4, v122
	v_cmp_lt_i32_e32 vcc, v120, v121
	s_nop 1
	v_cndmask_b32_e32 v120, v122, v120, vcc
	v_lshlrev_b32_e32 v120, 2, v120
	ds_bpermute_b32 v120, v120, v88
	s_waitcnt lgkmcnt(0)
	v_add_f32_e32 v88, v88, v120
	v_xor_b32_e32 v120, 8, v122
	v_cmp_lt_i32_e32 vcc, v120, v121
	s_nop 1
	v_cndmask_b32_e32 v120, v122, v120, vcc
	v_lshlrev_b32_e32 v120, 2, v120
	ds_bpermute_b32 v120, v120, v88
	s_waitcnt lgkmcnt(0)
	v_add_f32_e32 v88, v88, v120
	v_fmamk_f32 v88, v88, 0x3c000000, v118
	v_cmp_gt_f32_e32 vcc, s17, v88
	v_mul_f32_e32 v120, 0x4b800000, v88
	s_nop 0
	v_cndmask_b32_e32 v88, v88, v120, vcc
	v_rsq_f32_e32 v88, v88
	s_nop 0
	v_mul_f32_e32 v120, 0x45800000, v88
	v_cndmask_b32_e32 v88, v88, v120, vcc
	v_pk_mul_f32 v[82:83], v[82:83], v[88:89] op_sel_hi:[1,0]
	v_pk_mul_f32 v[84:85], v[84:85], v[88:89] op_sel_hi:[1,0]
	v_pk_mul_f32 v[78:79], v[78:79], v[88:89] op_sel_hi:[1,0]
	v_pk_mul_f32 v[80:81], v[80:81], v[88:89] op_sel_hi:[1,0]
	v_lshl_add_u64 v[120:121], v[92:93], 0, s[10:11]
	v_pk_mul_f32 v[78:79], v[158:159], v[78:79]
	v_pk_mul_f32 v[82:83], v[154:155], v[82:83]
	v_pk_mul_f32 v[84:85], v[156:157], v[84:85]
	v_pk_mul_f32 v[80:81], v[160:161], v[80:81]
	global_store_dwordx4 v[120:121], v[82:85], off
	global_store_dwordx4 v[120:121], v[78:81], off offset:16
	s_nop 0
	v_cvt_pk_bf16_f32 v82, v82, v83
	v_cvt_pk_bf16_f32 v83, v84, v85
	v_cvt_pk_bf16_f32 v84, v78, v79
	v_cvt_pk_bf16_f32 v85, v80, v81
	v_lshl_add_u64 v[78:79], v[94:95], 0, s[12:13]
	global_store_dwordx4 v[78:79], v[82:85], off
	v_lshl_add_u64 v[78:79], v[96:97], 0, s[10:11]
	s_waitcnt vmcnt(3)
	global_store_dwordx4 v[78:79], v[74:77], off
	global_store_dwordx4 v[78:79], v[70:73], off offset:16
	s_nop 0
	v_cvt_pk_bf16_f32 v74, v74, v75
	v_cvt_pk_bf16_f32 v75, v76, v77
	v_cvt_pk_bf16_f32 v76, v70, v71
	v_cvt_pk_bf16_f32 v77, v72, v73
	v_lshl_add_u64 v[70:71], v[98:99], 0, s[12:13]
	global_store_dwordx4 v[70:71], v[74:77], off
	s_cbranch_execnz .LBB0_486
	s_branch .LBB0_490

.LBB0_494:
	s_or_b64 exec, exec, s[22:23]
	s_ashr_i32 s5, s4, 31
	v_mov_b32_e32 v88, 0
	s_and_saveexec_b64 s[22:23], s[6:7]
	s_cbranch_execz .LBB0_496
	s_lshr_b32 s10, s5, 21
	s_add_i32 s10, s4, s10
	s_and_b32 s10, s10, 0x7fff800
	s_sub_i32 s10, s4, s10
	s_cmp_lt_i32 s4, 0x8000
	s_cselect_b32 s10, s10, s2
	v_readlane_b32 s24, v253, 7
	v_readlane_b32 s25, v253, 8
	v_lshl_or_b32 v162, s10, 5, v87
	v_ashrrev_i32_e32 v163, 31, v162
	s_nop 0
	v_lshl_add_u64 v[162:163], v[162:163], 2, s[24:25]
	global_load_dwordx2 v[162:163], v[162:163], off
	v_lshlrev_b32_e32 v88, 1, v86
	v_lshl_add_u64 v[120:121], s[12:13], 0, v[88:89]
	v_add_co_u32_e32 v120, vcc, 0x1000, v120
	s_nop 1
	v_addc_co_u32_e32 v121, vcc, 0, v121, vcc
	global_load_ushort v88, v[120:121], off offset:288
	s_waitcnt vmcnt(0)
	v_lshlrev_b32_e32 v88, 16, v88
.LBB0_496:
	s_or_b64 exec, exec, s[22:23]
	s_waitcnt vmcnt(1)
	v_lshlrev_b32_e32 v120, 16, v82
	v_pk_fma_f32 v[124:125], v[64:65], v[120:121], v[68:69] op_sel_hi:[1,0,1]
	v_pk_fma_f32 v[120:121], v[62:63], v[120:121], v[66:67] op_sel_hi:[1,0,1]
	s_waitcnt vmcnt(0)
	v_lshlrev_b32_e32 v126, 16, v78
	v_pk_fma_f32 v[124:125], v[32:33], v[126:127], v[124:125] op_sel_hi:[1,0,1]
	v_pk_fma_f32 v[120:121], v[30:31], v[126:127], v[120:121] op_sel_hi:[1,0,1]
	v_bfi_b32 v82, v91, 0, v82
	v_pk_fma_f32 v[124:125], v[4:5], v[82:83], v[124:125] op_sel_hi:[1,0,1]
	v_pk_fma_f32 v[120:121], v[2:3], v[82:83], v[120:121] op_sel_hi:[1,0,1]
	v_bfi_b32 v78, v91, 0, v78
	v_pk_fma_f32 v[124:125], v[36:37], v[78:79], v[124:125] op_sel_hi:[1,0,1]
	v_pk_fma_f32 v[120:121], v[34:35], v[78:79], v[120:121] op_sel_hi:[1,0,1]
	v_lshlrev_b32_e32 v78, 16, v83
	v_pk_fma_f32 v[124:125], v[8:9], v[78:79], v[124:125] op_sel_hi:[1,0,1]
	v_pk_fma_f32 v[120:121], v[6:7], v[78:79], v[120:121] op_sel_hi:[1,0,1]
	v_lshlrev_b32_e32 v78, 16, v79
	v_pk_fma_f32 v[124:125], v[40:41], v[78:79], v[124:125] op_sel_hi:[1,0,1]
	v_pk_fma_f32 v[120:121], v[38:39], v[78:79], v[120:121] op_sel_hi:[1,0,1]
	v_bfi_b32 v78, v91, 0, v83
	v_pk_fma_f32 v[82:83], v[12:13], v[78:79], v[124:125] op_sel_hi:[1,0,1]
	v_pk_fma_f32 v[120:121], v[10:11], v[78:79], v[120:121] op_sel_hi:[1,0,1]
	v_bfi_b32 v78, v91, 0, v79
	v_pk_fma_f32 v[82:83], v[44:45], v[78:79], v[82:83] op_sel_hi:[1,0,1]
	v_pk_fma_f32 v[78:79], v[42:43], v[78:79], v[120:121] op_sel_hi:[1,0,1]
	v_lshlrev_b32_e32 v120, 16, v84
	v_pk_fma_f32 v[82:83], v[16:17], v[120:121], v[82:83] op_sel_hi:[1,0,1]
	v_pk_fma_f32 v[78:79], v[14:15], v[120:121], v[78:79] op_sel_hi:[1,0,1]
	v_lshlrev_b32_e32 v120, 16, v80
	v_pk_fma_f32 v[82:83], v[48:49], v[120:121], v[82:83] op_sel_hi:[1,0,1]
	v_pk_fma_f32 v[78:79], v[46:47], v[120:121], v[78:79] op_sel_hi:[1,0,1]
	v_bfi_b32 v84, v91, 0, v84
	v_pk_fma_f32 v[82:83], v[20:21], v[84:85], v[82:83] op_sel_hi:[1,0,1]
	v_pk_fma_f32 v[78:79], v[18:19], v[84:85], v[78:79] op_sel_hi:[1,0,1]
	v_bfi_b32 v80, v91, 0, v80
	v_pk_fma_f32 v[82:83], v[52:53], v[80:81], v[82:83] op_sel_hi:[1,0,1]
	v_pk_fma_f32 v[78:79], v[50:51], v[80:81], v[78:79] op_sel_hi:[1,0,1]
	v_lshlrev_b32_e32 v80, 16, v85
	v_pk_fma_f32 v[82:83], v[24:25], v[80:81], v[82:83] op_sel_hi:[1,0,1]
	v_pk_fma_f32 v[78:79], v[22:23], v[80:81], v[78:79] op_sel_hi:[1,0,1]
	v_lshlrev_b32_e32 v80, 16, v81
	v_pk_fma_f32 v[82:83], v[56:57], v[80:81], v[82:83] op_sel_hi:[1,0,1]
	v_pk_fma_f32 v[78:79], v[54:55], v[80:81], v[78:79] op_sel_hi:[1,0,1]
	v_bfi_b32 v80, v91, 0, v85
	v_pk_fma_f32 v[82:83], v[28:29], v[80:81], v[82:83] op_sel_hi:[1,0,1]
	v_pk_fma_f32 v[78:79], v[26:27], v[80:81], v[78:79] op_sel_hi:[1,0,1]
	v_bfi_b32 v80, v91, 0, v81
	v_pk_fma_f32 v[82:83], v[60:61], v[80:81], v[82:83] op_sel_hi:[1,0,1]
	v_pk_fma_f32 v[78:79], v[58:59], v[80:81], v[78:79] op_sel_hi:[1,0,1]
	v_min_f32_e32 v84, 0, v82
	v_min_f32_e32 v80, 0, v78
	v_mul_f32_e64 v78, |v78|, s21
	v_min_f32_e32 v81, 0, v79
	v_mul_f32_e64 v79, |v79|, s21
	v_mul_f32_e64 v82, |v82|, s21
	v_min_f32_e32 v85, 0, v83
	v_mul_f32_e64 v83, |v83|, s21
	v_exp_f32_e32 v78, v78
	v_exp_f32_e32 v79, v79
	v_exp_f32_e32 v82, v82
	v_exp_f32_e32 v83, v83
	v_add_f32_e32 v78, 1.0, v78
	v_add_f32_e32 v79, 1.0, v79
	v_add_f32_e32 v82, 1.0, v82
	v_add_f32_e32 v83, 1.0, v83
	v_log_f32_e32 v78, v78
	v_log_f32_e32 v79, v79
	v_log_f32_e32 v82, v82
	v_log_f32_e32 v83, v83
	s_lshl_b64 s[10:11], s[4:5], 10
	v_pk_fma_f32 v[78:79], v[78:79], s[16:17], v[80:81] op_sel_hi:[1,0,1]
	v_pk_fma_f32 v[82:83], v[82:83], s[16:17], v[84:85] op_sel_hi:[1,0,1]
	s_nop 0
	v_pk_mul_f32 v[80:81], v[82:83], s[20:21] op_sel_hi:[1,0]
	v_pk_mul_f32 v[78:79], v[78:79], s[20:21] op_sel_hi:[1,0]
	v_lshl_add_u64 v[82:83], v[100:101], 0, s[10:11]
	global_store_dwordx4 v[82:83], v[78:81], off
	v_and_b32_e32 v83, 0xffff0000, v75
	v_lshlrev_b32_e32 v82, 16, v75
	v_and_b32_e32 v79, 0xffff0000, v70
	v_lshlrev_b32_e32 v78, 16, v70
	v_mul_f32_e32 v70, v79, v79
	v_and_b32_e32 v81, 0xffff0000, v74
	v_lshlrev_b32_e32 v80, 16, v74
	v_pk_fma_f32 v[84:85], v[78:79], v[78:79], v[70:71] op_sel_hi:[1,1,0]
	v_and_b32_e32 v75, 0xffff0000, v71
	v_lshlrev_b32_e32 v74, 16, v71
	v_pk_fma_f32 v[70:71], v[74:75], v[74:75], v[84:85]
	v_mul_f32_e32 v84, v75, v75
	v_pk_add_f32 v[120:121], v[84:85], v[70:71] op_sel_hi:[0,1]
	v_and_b32_e32 v71, 0xffff0000, v72
	v_lshlrev_b32_e32 v70, 16, v72
	v_pk_mul_f32 v[124:125], v[80:81], v[80:81]
	v_pk_fma_f32 v[120:121], v[70:71], v[70:71], v[120:121]
	v_mul_f32_e32 v72, v71, v71
	v_pk_mul_f32 v[126:127], v[82:83], v[82:83]
	v_pk_add_f32 v[130:131], v[72:73], v[120:121] op_sel_hi:[0,1]
	v_add_f32_e32 v72, v124, v125
	v_and_b32_e32 v85, 0xffff0000, v76
	v_lshlrev_b32_e32 v84, 16, v76
	v_add_f32_e32 v72, v126, v72
	v_pk_mul_f32 v[128:129], v[84:85], v[84:85]
	v_add_f32_e32 v72, v127, v72
	v_and_b32_e32 v121, 0xffff0000, v77
	v_lshlrev_b32_e32 v120, 16, v77
	v_add_f32_e32 v72, v128, v72
	v_pk_mul_f32 v[132:133], v[120:121], v[120:121]
	v_add_f32_e32 v72, v129, v72
	v_and_b32_e32 v77, 0xffff0000, v73
	v_lshlrev_b32_e32 v76, 16, v73
	v_add_f32_e32 v72, v132, v72
	v_add_f32_e32 v123, v133, v72
	v_pk_fma_f32 v[72:73], v[76:77], v[76:77], v[130:131]
	v_mul_f32_e32 v124, v77, v77
	v_pk_add_f32 v[72:73], v[124:125], v[72:73] op_sel_hi:[0,1]
	v_and_b32_e32 v73, 64, v122
	v_add_u32_e32 v73, 64, v73
	v_xor_b32_e32 v124, 32, v122
	v_cmp_lt_i32_e32 vcc, v124, v73
	v_mul_f32_e32 v128, v88, v88
	v_mov_b32_e32 v129, v72
	v_cndmask_b32_e32 v124, v122, v124, vcc
	v_lshlrev_b32_e32 v124, 2, v124
	ds_bpermute_b32 v125, v124, v123
	ds_bpermute_b32 v131, v124, v72
	ds_bpermute_b32 v130, v124, v128
	v_xor_b32_e32 v124, 16, v122
	v_cmp_lt_i32_e32 vcc, v124, v73
	s_waitcnt lgkmcnt(2)
	v_add_f32_e32 v123, v123, v125
	v_cndmask_b32_e32 v124, v122, v124, vcc
	v_lshlrev_b32_e32 v124, 2, v124
	ds_bpermute_b32 v125, v124, v123
	s_waitcnt lgkmcnt(0)
	v_add_f32_e32 v123, v123, v125
	v_xor_b32_e32 v125, 8, v122
	v_cmp_lt_i32_e32 vcc, v125, v73
	s_nop 1
	v_cndmask_b32_e32 v125, v122, v125, vcc
	v_lshlrev_b32_e32 v127, 2, v125
	ds_bpermute_b32 v125, v127, v123
	s_waitcnt lgkmcnt(0)
	v_add_f32_e32 v123, v123, v125
	v_xor_b32_e32 v125, 4, v122
	v_cmp_lt_i32_e32 vcc, v125, v73
	s_nop 1
	v_cndmask_b32_e32 v125, v122, v125, vcc
	v_lshlrev_b32_e32 v132, 2, v125
	ds_bpermute_b32 v125, v132, v123
	s_waitcnt lgkmcnt(0)
	v_add_f32_e32 v123, v123, v125
	v_xor_b32_e32 v125, 2, v122
	v_cmp_lt_i32_e32 vcc, v125, v73
	s_nop 1
	v_cndmask_b32_e32 v125, v122, v125, vcc
	v_lshlrev_b32_e32 v133, 2, v125
	ds_bpermute_b32 v125, v133, v123
	s_waitcnt lgkmcnt(0)
	v_add_f32_e32 v125, v123, v125
	v_xor_b32_e32 v123, 1, v122
	v_cmp_lt_i32_e32 vcc, v123, v73
	s_nop 1
	v_cndmask_b32_e32 v73, v122, v123, vcc
	v_lshlrev_b32_e32 v134, 2, v73
	v_pk_add_f32 v[72:73], v[128:129], v[130:131]
	ds_bpermute_b32 v123, v124, v73
	ds_bpermute_b32 v122, v124, v72
	ds_bpermute_b32 v126, v134, v125
	s_waitcnt lgkmcnt(1)
	v_pk_add_f32 v[72:73], v[72:73], v[122:123]
	ds_bpermute_b32 v123, v127, v73
	ds_bpermute_b32 v122, v127, v72
	s_waitcnt lgkmcnt(0)
	v_pk_add_f32 v[72:73], v[72:73], v[122:123]
	ds_bpermute_b32 v123, v132, v73
	ds_bpermute_b32 v122, v132, v72
	s_waitcnt lgkmcnt(0)
	v_pk_add_f32 v[72:73], v[72:73], v[122:123]
	ds_bpermute_b32 v123, v133, v73
	ds_bpermute_b32 v122, v133, v72
	s_waitcnt lgkmcnt(0)
	v_pk_add_f32 v[72:73], v[72:73], v[122:123]
	ds_bpermute_b32 v123, v134, v73
	ds_bpermute_b32 v122, v134, v72
	s_and_saveexec_b64 s[12:13], s[0:1]
	s_cbranch_execz .LBB0_498
	v_add_f32_e32 v125, v125, v126
	v_fmamk_f32 v125, v125, 0x3b2aaaab, v118
	v_mul_f32_e32 v126, 0x4b800000, v125
	v_cmp_gt_f32_e32 vcc, s17, v125
	s_nop 1
	v_cndmask_b32_e32 v125, v125, v126, vcc
	v_rsq_f32_e32 v125, v125
	s_nop 0
	v_mul_f32_e32 v126, 0x45800000, v125
	v_cndmask_b32_e32 v126, v125, v126, vcc
	v_pk_mul_f32 v[80:81], v[126:127], v[80:81] op_sel_hi:[0,1]
	v_pk_mul_f32 v[82:83], v[126:127], v[82:83] op_sel_hi:[0,1]
	v_pk_mul_f32 v[84:85], v[126:127], v[84:85] op_sel_hi:[0,1]
	v_pk_mul_f32 v[120:121], v[126:127], v[120:121] op_sel_hi:[0,1]
	v_pk_mul_f32 v[80:81], v[80:81], v[136:137]
	v_pk_mul_f32 v[82:83], v[82:83], v[138:139]
	v_pk_mul_f32 v[84:85], v[84:85], v[140:141]
	v_pk_mul_f32 v[120:121], v[120:121], v[142:143]
	v_cvt_pk_bf16_f32 v80, v80, v81
	v_cvt_pk_bf16_f32 v81, v82, v83
	v_cvt_pk_bf16_f32 v82, v84, v85
	v_cvt_pk_bf16_f32 v83, v120, v121
	v_mad_i64_i32 v[84:85], s[10:11], s4, v119, v[102:103]
	global_store_dwordx4 v[84:85], v[80:83], off
.LBB0_498:
	s_or_b64 exec, exec, s[12:13]
	s_waitcnt lgkmcnt(0)
	v_pk_add_f32 v[72:73], v[72:73], v[122:123]
	s_nop 0
	v_pk_fma_f32 v[72:73], v[72:73], s[18:19], v[118:119] op_sel_hi:[1,1,0]
	s_nop 0
	v_cmp_gt_f32_e64 s[12:13], s17, v73
	v_cmp_gt_f32_e32 vcc, s17, v72
	s_and_saveexec_b64 s[22:23], s[6:7]
	s_cbranch_execz .LBB0_500
	v_mul_f32_e32 v80, 0x4b800000, v73
	v_cndmask_b32_e64 v73, v73, v80, s[12:13]
	v_rsq_f32_e32 v73, v73
	s_lshl_b64 s[24:25], s[4:5], 8
	v_readlane_b32 s36, v254, 12
	s_lshl_b64 s[10:11], s[24:25], 2
	v_mul_f32_e32 v80, 0x45800000, v73
	v_cndmask_b32_e64 v84, v73, v80, s[12:13]
	v_readlane_b32 s38, v254, 14
	v_readlane_b32 s39, v254, 15
	s_add_u32 s12, s38, s10
	s_addc_u32 s13, s39, s11
	s_add_i32 s14, s4, 0xffff8000
	v_readlane_b32 s48, v254, 24
	s_lshl_b64 s[10:11], s[14:15], 10
	v_readlane_b32 s49, v254, 25
	s_add_u32 s10, s48, s10
	v_pk_mul_f32 v[74:75], v[84:85], v[74:75] op_sel_hi:[0,1]
	v_pk_mul_f32 v[70:71], v[84:85], v[70:71] op_sel_hi:[0,1]
	s_addc_u32 s11, s49, s11
	v_pk_mul_f32 v[78:79], v[84:85], v[78:79] op_sel_hi:[0,1]
	s_cmp_lt_i32 s4, 0x8000
	s_cselect_b32 s13, s13, s11
	s_cselect_b32 s12, s12, s10
	v_readlane_b32 s37, v254, 13
	v_readlane_b32 s40, v254, 16
	v_readlane_b32 s41, v254, 17
	v_readlane_b32 s42, v254, 18
	v_readlane_b32 s43, v254, 19
	v_readlane_b32 s44, v254, 20
	v_readlane_b32 s45, v254, 21
	v_readlane_b32 s46, v254, 22
	v_readlane_b32 s47, v254, 23
	v_readlane_b32 s50, v254, 26
	v_readlane_b32 s51, v254, 27
	v_pk_mul_f32 v[122:123], v[74:75], v[146:147]
	v_pk_mul_f32 v[74:75], v[70:71], v[148:149]
	v_pk_mul_f32 v[70:71], v[84:85], v[76:77] op_sel_hi:[0,1]
	v_pk_mul_f32 v[120:121], v[78:79], v[144:145]
	v_pk_mul_f32 v[76:77], v[70:71], v[150:151]
	v_lshlrev_b32_e32 v70, 2, v90
	global_store_dwordx4 v70, v[120:123], s[12:13]
	global_store_dwordx4 v70, v[74:77], s[12:13] offset:16
	v_cvt_pk_bf16_f32 v78, v120, v121
	v_cvt_pk_bf16_f32 v79, v122, v123
	v_cvt_pk_bf16_f32 v80, v74, v75
	v_cvt_pk_bf16_f32 v81, v76, v77
	v_lshl_add_u64 v[70:71], s[24:25], 1, v[104:105]
	global_store_dwordx4 v[70:71], v[78:81], off
.LBB0_500:
	s_or_b64 exec, exec, s[22:23]
	v_mul_f32_e32 v70, 0x4b800000, v72
	v_cndmask_b32_e32 v70, v72, v70, vcc
	v_rsq_f32_e32 v70, v70
	s_nop 0
	v_mul_f32_e32 v71, 0x45800000, v70
	v_cndmask_b32_e32 v70, v70, v71, vcc
	v_mul_f32_e32 v70, v88, v70
	v_mul_f32_e32 v70, v70, v152
	ds_bpermute_b32 v71, v124, v70
	s_and_saveexec_b64 s[12:13], s[6:7]
	s_cbranch_execz .LBB0_485
	s_lshr_b32 s10, s5, 21
	s_add_i32 s10, s4, s10
	s_and_b32 s10, s10, 0x7fff800
	s_sub_i32 s10, s4, s10
	s_add_i32 s14, s4, 0xffff8000
	s_cmp_lt_i32 s4, 0x8000
	s_cselect_b32 s10, s10, s2
	v_lshl_or_b32 v72, s10, 5, v87
	v_readlane_b32 s36, v253, 3
	v_ashrrev_i32_e32 v73, 31, v72
	v_readlane_b32 s40, v253, 7
	v_readlane_b32 s41, v253, 8
	v_readlane_b32 s37, v253, 4
	v_readlane_b32 s38, v253, 5
	v_lshl_add_u64 v[72:73], v[72:73], 2, s[40:41]
	v_readlane_b32 s39, v253, 6
	v_readlane_b32 s42, v253, 9
	v_readlane_b32 s43, v253, 10
	v_readlane_b32 s44, v253, 11
	v_readlane_b32 s45, v253, 12
	v_readlane_b32 s46, v253, 13
	v_readlane_b32 s47, v253, 14
	v_readlane_b32 s48, v253, 15
	v_readlane_b32 s49, v253, 16
	v_readlane_b32 s50, v253, 17
	v_readlane_b32 s51, v253, 18
	v_readlane_b32 s36, v254, 12
	s_cselect_b32 s11, s5, 0
	s_cselect_b32 s10, s4, s14
	v_readlane_b32 s40, v254, 16
	v_readlane_b32 s41, v254, 17
	v_readlane_b32 s50, v254, 26
	v_readlane_b32 s51, v254, 27
	s_cselect_b32 s14, s41, s51
	s_cselect_b32 s22, s40, s50
	s_lshl_b64 s[10:11], s[10:11], 7
	s_add_u32 s10, s22, s10
	v_lshlrev_b32_e32 v74, 2, v86
	s_addc_u32 s11, s14, s11
	s_lshl_b64 s[22:23], s[4:5], 6
	v_readlane_b32 s37, v254, 13
	v_readlane_b32 s38, v254, 14
	v_readlane_b32 s39, v254, 15
	v_readlane_b32 s42, v254, 18
	v_readlane_b32 s43, v254, 19
	v_readlane_b32 s44, v254, 20
	v_readlane_b32 s45, v254, 21
	v_readlane_b32 s46, v254, 22
	v_readlane_b32 s47, v254, 23
	v_readlane_b32 s48, v254, 24
	v_readlane_b32 s49, v254, 25
	s_waitcnt lgkmcnt(0)
	v_mul_f32_e32 v71, v163, v71
	v_cndmask_b32_e64 v71, v71, -v71, s[8:9]
	v_fmac_f32_e32 v71, v70, v162
	global_store_dword v74, v71, s[10:11]
	v_cvt_pk_bf16_f32 v72, v71, s0
	v_lshl_add_u64 v[70:71], v[106:107], 0, s[22:23]
	global_store_short v[70:71], v72, off
	s_branch .LBB0_485
